# v5: split barrier (early prompt arrive incl. phase 1, per-seam sample words, async polls), write-through prologue weight stores, epilogue waits de-serialised
# speedup vs baseline: 1.0363x; 1.0060x over previous
; #define PG8_WAIT_V(n) asm volatile("s_waitcnt vmcnt(" #n ")" ::: "memory")
; #define PG8_BAR __builtin_amdgcn_s_barrier()
; __device__ __forceinline__ unsigned xb_ld(unsigned* p)              { return __hip_atomic_load(p, __ATOMIC_RELAXED, __HIP_MEMORY_SCOPE_AGENT); }
; __device__ __forceinline__ unsigned xb_add(unsigned* p, unsigned v) { return __hip_atomic_fetch_add(p, v, __ATOMIC_RELAXED, __HIP_MEMORY_SCOPE_AGENT); }
; template <class Epi, class Sched, bool ALIGN_EPI = false, bool SP2 = false>
; __device__ __forceinline__ void gemm_phase(PG8_LAS unsigned char* lds, const Gemm g, const Sched& S, const Epi& E, const int tid) {
;     ...
;     PG8_WAIT_V(0);
;     if constexpr (!ALIGN_EPI) { if (wr == 0) PG8_BAR; }
;     PG8_BAR;
; __device__ __forceinline__ void group_barrier(unsigned* ctl, int x, unsigned target, bool coloc) {
;     asm volatile("s_waitcnt vmcnt(0)" ::: "memory");
;     __syncthreads();
;     if (threadIdx.x == 0) {
;         if (!coloc) { __builtin_amdgcn_fence(__ATOMIC_RELEASE, "agent"); asm volatile("s_waitcnt vmcnt(0)" ::: "memory"); }
;         (void)xb_add(&ctl[GB_CNT(x)], 1u);
; __global__ void __launch_bounds__(NWAVES * 64, 2) hybrid_fwd(Args args) {
;     ...
;             else if (local) { unsigned* ctl = (unsigned*)(args.ws + WS_CTL); const int x = blockIdx.x & 7; ++gbn;
;                 const unsigned mk = xb_ld(&ctl[GB_MASK(x)]); group_barrier(ctl, x, 32u * gbn, (mk & (mk - 1u)) == 0u && mk != 0u); }
.LBB0_57:
	s_waitcnt vmcnt(0)
	s_mov_b64 s[38:39], s[40:41]
	v_readlane_b32 s56, v254, 55
	s_mov_b32 s37, 0x18000
	s_mov_b32 s57, 0x8000
	s_mov_b32 s58, 0x20000
	s_mov_b32 s59, 0x30000
	s_mov_b32 s68, s42
	s_mov_b32 s69, s43
	v_readlane_b32 s70, v254, 58
	s_barrier
	s_cmp_lt_u32 s38, 1
	s_cbranch_scc1 .Lap_skip_up
	s_mov_b32 s99, 1
	v_cmp_eq_u32_e32 vcc, 0, v135
	s_and_saveexec_b64 s[100:101], vcc
	s_cbranch_execz .Lap_done_up
	s_cmp_lg_u32 s38, 1
	s_cbranch_scc1 .Lap_known_up
	v_readlane_b32 vcc_lo, v253, 52
	v_readlane_b32 vcc_hi, v253, 53
	s_nop 4
	global_load_dword v1, v129, vcc sc1
	s_waitcnt vmcnt(0)
	v_bcnt_u32_b32 v1, v1, 0
	s_nop 0
	v_readfirstlane_b32 s98, v1
.Lap_known_up:
	s_cmp_eq_u32 s98, 1
	s_cbranch_scc1 .Lap_nowb_up
	buffer_wbl2 sc1
	s_waitcnt vmcnt(0)

; __global__ void __launch_bounds__(NWAVES * 64, 2) hybrid_fwd(Args args) {
;     ...
;                   if (nk > 0) { EwRow r0, r1, r2;
;                     { const int ma = EW_ROW(0); ew_load(r0, X16 + (size_t)ma * 2 * DM, OB + (size_t)ma * OP, lane); }
;                     { const int kb = 1 < nk ? 1 : 0; const int mb = EW_ROW(kb); ew_load(r1, X16 + (size_t)mb * 2 * DM, OB + (size_t)mb * OP, lane); }
; #pragma unroll 1
;                     for (int k = 0; k < nk; ++k) {
;                         { const int kc = k + 2 < nk ? k + 2 : k; const int mc = EW_ROW(kc); ew_load(r2, X16 + (size_t)mc * 2 * DM, OB + (size_t)mc * OP, lane); }
;                         const int m = EW_ROW(k);
;                         ew_finish(r0, gg, X + (size_t)m * DM, X16 + (size_t)m * 2 * DM, dst16, RS + m, write_xn, lane);
;                         r0 = r1; r1 = r2;
.LBB0_428:
	s_add_i32 s10, s19, 2
	s_waitcnt vmcnt(0)
	s_cmp_eq_u32 s19, 3
	s_cbranch_scc0 .Lrs_nopoll
	s_cmp_eq_u32 s17, 9
	s_cbranch_scc0 .Lrs_nopoll
	v_readlane_b32 s100, v253, 54
	v_readlane_b32 s101, v253, 55
	s_lshl_b32 vcc_lo, s69, 2
	s_add_u32 vcc_lo, vcc_lo, 0x2000
	s_add_u32 s100, s100, vcc_lo
	s_addc_u32 s101, s101, 0
	global_load_dword v255, v129, s[100:101] sc1
	s_mov_b32 s101, 0
.Lrs_nopoll:
	v_mov_b64_e32 v[16:17], v[36:37]
	s_waitcnt vmcnt(2)
	v_mov_b64_e32 v[20:21], v[44:45]
	s_waitcnt vmcnt(1)
	v_mov_b64_e32 v[24:25], v[40:41]
	s_waitcnt vmcnt(0)
	v_mov_b64_e32 v[28:29], v[32:33]
	s_cmp_lt_i32 s10, s17
	v_mov_b64_e32 v[18:19], v[38:39]
	v_mov_b64_e32 v[22:23], v[46:47]
	v_mov_b64_e32 v[26:27], v[42:43]
	v_mov_b64_e32 v[30:31], v[34:35]
	s_cselect_b32 s11, s10, s19
	s_mov_b64 s[12:13], -1
	s_and_b64 vcc, exec, s[0:1]
	s_cbranch_vccz .LBB0_430
	s_mul_i32 s10, s11, s16
	s_add_i32 s10, s10, s2
	s_mov_b64 s[12:13], 0

; __global__ void __launch_bounds__(NWAVES * 64, 2) hybrid_fwd(Args args) {
;     ...
;                   if (nk > 0) { EwRow r0, r1, r2;
;                     { const int ma = EW_ROW(0); ew_load(r0, X16 + (size_t)ma * 2 * DM, OB + (size_t)ma * OP, lane); }
;                     { const int kb = 1 < nk ? 1 : 0; const int mb = EW_ROW(kb); ew_load(r1, X16 + (size_t)mb * 2 * DM, OB + (size_t)mb * OP, lane); }
; #pragma unroll 1
;                     for (int k = 0; k < nk; ++k) {
;                         { const int kc = k + 2 < nk ? k + 2 : k; const int mc = EW_ROW(kc); ew_load(r2, X16 + (size_t)mc * 2 * DM, OB + (size_t)mc * OP, lane); }
;                         const int m = EW_ROW(k);
;                         ew_finish(r0, gg, X + (size_t)m * DM, X16 + (size_t)m * 2 * DM, dst16, RS + m, write_xn, lane);
.Lres_ws:
	s_cmp_eq_u32 s101, -1
	s_cbranch_scc1 .Lws_skip_rs
	v_readfirstlane_b32 vcc_hi, v255
	s_cmp_ge_u32 vcc_hi, 32
	s_cbranch_scc1 .Lws_done_rs
	s_mov_b32 vcc_lo, s69
	s_cmp_eq_u32 vcc_lo, 0
	s_cbranch_scc1 .Lws_done_rs
	v_readlane_b32 s100, v253, 54
	v_readlane_b32 s101, v253, 55
	s_lshl_b32 vcc_lo, vcc_lo, 2
	s_add_u32 vcc_lo, vcc_lo, 0x2000
	s_add_u32 s100, s100, vcc_lo
	s_addc_u32 s101, s101, 0
	s_mov_b32 m0, 0

; #define PG8_WAIT_V(n) asm volatile("s_waitcnt vmcnt(" #n ")" ::: "memory")
; #define PG8_BAR __builtin_amdgcn_s_barrier()
; __device__ __forceinline__ unsigned xb_ld(unsigned* p)              { return __hip_atomic_load(p, __ATOMIC_RELAXED, __HIP_MEMORY_SCOPE_AGENT); }
; template <class Epi, class Sched, bool ALIGN_EPI = false, bool SP2 = false>
; __device__ __forceinline__ void gemm_phase(PG8_LAS unsigned char* lds, const Gemm g, const Sched& S, const Epi& E, const int tid) {
;     ...
;     PG8_WAIT_V(0);
;     if constexpr (!ALIGN_EPI) { if (wr == 0) PG8_BAR; }
;     PG8_BAR;
; __global__ void __launch_bounds__(NWAVES * 64, 2) hybrid_fwd(Args args) {
;     ...
;             else if (local) { unsigned* ctl = (unsigned*)(args.ws + WS_CTL); const int x = blockIdx.x & 7; ++gbn;
;                 const unsigned mk = xb_ld(&ctl[GB_MASK(x)]); group_barrier(ctl, x, 32u * gbn, (mk & (mk - 1u)) == 0u && mk != 0u); }
.LBB0_492:
	s_waitcnt vmcnt(0)
	v_readlane_b32 s80, v254, 56
	v_readlane_b32 s38, v254, 59
	v_readlane_b32 s81, v254, 57
	v_readlane_b32 s39, v254, 60
	v_readlane_b32 s56, v254, 55
	s_barrier
	s_cmp_lt_u32 s38, 1
	s_cbranch_scc1 .Lap_skip_pl
	s_mov_b32 s99, 1
	v_cmp_eq_u32_e32 vcc, 0, v135
	s_and_saveexec_b64 s[100:101], vcc
	s_cbranch_execz .Lap_done_pl
	s_cmp_lg_u32 s38, 1
	s_cbranch_scc1 .Lap_known_pl
	v_readlane_b32 vcc_lo, v253, 52
	v_readlane_b32 vcc_hi, v253, 53
	s_nop 4
	global_load_dword v1, v129, vcc sc1
	s_waitcnt vmcnt(0)
	v_bcnt_u32_b32 v1, v1, 0
	s_nop 0
	v_readfirstlane_b32 s98, v1

; #define LAS __attribute__((address_space(3)))
; __device__ __forceinline__ unsigned pk2(float lo, float hi) { return f2bf(lo) | (f2bf(hi) << 16); }
; #define LDS_WAIT() asm volatile("s_waitcnt lgkmcnt(0)" ::: "memory")
; __device__ __forceinline__ void fold_item(const float* __restrict__ W, bf16* __restrict__ WT, const float* __restrict__ wp, const float* __restrict__ ps, LAS float* scr, int item4, int lane) {
;     ...
; #pragma unroll 2
;     for (int i = 0; i < 8; ++i) { const int kl = 2 * i + (lane >> 5); const LAS float* wr = wpL + kl * 64; float a = 0.f;
; #pragma unroll 16
;         for (int d = 0; d < 64; ++d) a += wr[d] * scr[d * 33 + n];
;         scr2[kl * 33 + n] = a; }
;     LDS_WAIT();
;     { const int ch = lane >> 5; const LAS float* s = scr2 + (8 * ch) * 33 + n;
;         v4u o; o.x = pk2(s[0 * 33], s[1 * 33]); o.y = pk2(s[2 * 33], s[3 * 33]); o.z = pk2(s[4 * 33], s[5 * 33]); o.w = pk2(s[6 * 33], s[7 * 33]);
;         *(v4u*)(WT + (size_t)(n0 + n) * (K + WPAD) + k0 + 16 * q + 8 * ch) = o; }
.LBB0_523:
	ds_read2_b32 v[34:35], v7 offset1:33
	ds_read2_b32 v[38:39], v7 offset0:66 offset1:99
	ds_read2_b32 v[40:41], v7 offset0:132 offset1:165
	ds_read2_b32 v[42:43], v7 offset0:198 offset1:231
	v_add_u32_e32 v8, s8, v3
	v_add_u32_e32 v15, 0x400, v7
	ds_read_b128 v[16:19], v8
	ds_read_b128 v[20:23], v8 offset:16
	ds_read_b128 v[24:27], v8 offset:32
	ds_read_b128 v[28:31], v8 offset:48
	ds_read2_b32 v[44:45], v15 offset0:8 offset1:41
	ds_read2_b32 v[46:47], v15 offset0:74 offset1:107
	ds_read2_b32 v[48:49], v15 offset0:140 offset1:173
	ds_read2_b32 v[50:51], v15 offset0:206 offset1:239
	s_waitcnt lgkmcnt(7)
	v_fmac_f32_e32 v6, v16, v34
	v_fmac_f32_e32 v6, v17, v35
	v_fmac_f32_e32 v6, v18, v38
	v_fmac_f32_e32 v6, v19, v39
	s_waitcnt lgkmcnt(6)
	v_fmac_f32_e32 v6, v20, v40
	v_fmac_f32_e32 v6, v21, v41
	v_fmac_f32_e32 v6, v22, v42
	v_fmac_f32_e32 v6, v23, v43
	s_waitcnt lgkmcnt(3)
	v_fmac_f32_e32 v6, v24, v44
	v_fmac_f32_e32 v6, v25, v45
	s_waitcnt lgkmcnt(2)
	v_fmac_f32_e32 v6, v26, v46
	v_fmac_f32_e32 v6, v27, v47
	s_waitcnt lgkmcnt(1)
	v_fmac_f32_e32 v6, v28, v48
	v_fmac_f32_e32 v6, v29, v49
	s_add_i32 s8, s8, 64
	s_waitcnt lgkmcnt(0)
	v_fmac_f32_e32 v6, v30, v50
	v_add_u32_e32 v7, 0x840, v7
	s_cmpk_lg_i32 s8, 0x100
	v_fmac_f32_e32 v6, v31, v51
	s_cbranch_scc1 .LBB0_523
	v_or_b32_e32 v7, s7, v10
	s_add_i32 s1, s1, 2
	v_mad_u64_u32 v[16:17], s[8:9], v7, s33, v[2:3]
	v_add_u32_e32 v5, 0x400, v5
	s_cmp_eq_u32 s1, 8
	v_add_u32_e32 v3, 0x400, v3
	ds_write_b32 v16, v6 offset:8448
	s_cbranch_scc0 .LBB0_520
	s_waitcnt lgkmcnt(0)
	v_add_u32_e32 v3, 0x2000, v9
	ds_read2_b32 v[6:7], v3 offset0:64 offset1:97
	ds_read2_b32 v[18:19], v3 offset0:130 offset1:163
	s_mul_hi_i32 s1, s6, 0x1800000
	s_mul_i32 s6, s6, 0x1800000
	s_add_u32 s6, s34, s6
	s_waitcnt lgkmcnt(1)
	v_bfe_u32 v5, v6, 16, 1
	v_add3_u32 v5, v6, v5, s90
	v_bfe_u32 v6, v7, 16, 1
	v_lshrrev_b32_e32 v5, 16, v5
	v_add3_u32 v6, v7, v6, s90
	v_and_or_b32 v16, v6, s91, v5
	s_waitcnt lgkmcnt(0)
	v_bfe_u32 v5, v18, 16, 1
	v_add3_u32 v5, v18, v5, s90
	ds_read2_b32 v[6:7], v3 offset0:196 offset1:229
	v_lshrrev_b32_e32 v3, 16, v5
	v_bfe_u32 v5, v19, 16, 1
	v_add3_u32 v5, v19, v5, s90
	v_and_or_b32 v17, v5, s91, v3
	v_add_u32_e32 v5, 0x2400, v9
	ds_read2_b32 v[20:21], v5 offset0:6 offset1:39
	s_waitcnt lgkmcnt(1)
	v_bfe_u32 v3, v6, 16, 1
	v_add3_u32 v3, v6, v3, s90
	v_bfe_u32 v5, v7, 16, 1
	v_or_b32_e32 v6, s4, v0
	v_lshrrev_b32_e32 v3, 16, v3
	v_add3_u32 v5, v7, v5, s90
	v_ashrrev_i32_e32 v7, 31, v6
	s_addc_u32 s7, s35, s1
	v_and_or_b32 v18, v5, s91, v3
	s_waitcnt lgkmcnt(0)
	v_bfe_u32 v3, v20, 16, 1
	v_lshlrev_b64 v[6:7], 11, v[6:7]
	v_add3_u32 v3, v20, v3, s90
	v_bfe_u32 v5, v21, 16, 1
	v_lshl_add_u64 v[6:7], s[6:7], 0, v[6:7]
	s_ashr_i32 s1, s0, 31
	v_lshrrev_b32_e32 v3, 16, v3
	v_add3_u32 v5, v21, v5, s90
	v_lshl_add_u64 v[6:7], s[0:1], 1, v[6:7]
	s_lshl_b32 s84, s5, 1
	v_and_or_b32 v19, v5, s91, v3
	v_lshl_add_u64 v[6:7], v[6:7], 0, s[84:85]
	v_mov_b32_e32 v5, v129
	v_lshl_add_u64 v[6:7], v[6:7], 0, v[4:5]
	v_add_co_u32_e32 v6, vcc, 0x680000, v6
	s_add_i32 s10, s10, s93
	s_nop 0
	v_addc_co_u32_e32 v7, vcc, 0, v7, vcc
	global_store_dwordx4 v[6:7], v[16:19], off sc1
	s_waitcnt lgkmcnt(0)
	s_cmpk_gt_i32 s10, 0x3ff
	s_cbranch_scc0 .LBB0_517

; __device__ __forceinline__ unsigned cvt_pk_bf16(float lo, float hi) { unsigned r; asm volatile("v_cvt_pk_bf16_f32 %0, %1, %2" : "=v"(r) : "v"(lo), "v"(hi)); return r; }
; #define LAS __attribute__((address_space(3)))
; __device__ __forceinline__ void tr_store(const float (&v)[32], const TrDesc& d, LAS float* scr, int lane) {
;     ...
;     const int c = lane & 7;
; #pragma unroll
;     for (int j = 0; j < 4; ++j) { const int n = (lane >> 3) + 8 * j; const LAS float* s = scr + (8 * c) * 33 + n;
;         v4u o; o.x = pg8::cvt_pk_bf16(s[0 * 33], s[1 * 33]); o.y = pg8::cvt_pk_bf16(s[2 * 33], s[3 * 33]); o.z = pg8::cvt_pk_bf16(s[4 * 33], s[5 * 33]); o.w = pg8::cvt_pk_bf16(s[6 * 33], s[7 * 33]);
;         *(v4u*)(d.WT + (size_t)(d.n0 + n) * (d.K + WPAD) + d.k0 + 8 * c) = o; }
; __global__ void __launch_bounds__(NWAVES * 64, 2) hybrid_fwd(Args args) {
;     ...
;                 for (; it < I_ALL; it += TSTEP) {
;                     { const int q = it + 2 * TSTEP < I_ALL ? it + 2 * TSTEP : it; TR_DECODE(q, d2); }
;                     tr_load(vc, d2, lane);
;                     tr_store(va, d0, scr, lane);
; #pragma unroll
;                     for (int i = 0; i < 32; ++i) { va[i] = vb[i]; vb[i] = vc[i]; }
;                     d0 = d1; d1 = d2;
;                 }
.LBB0_552:
	ds_write_b32 v73, v0 offset:8184
	s_waitcnt lgkmcnt(0)
	v_add_u32_e32 v6, s2, v68
	ds_read2_b32 v[0:1], v69 offset1:33
	v_mul_hi_i32_i24_e32 v7, s4, v6
	v_mul_i32_i24_e32 v6, s4, v6
	s_waitcnt lgkmcnt(0)
	v_cvt_pk_bf16_f32 v0, v0, v1
	ds_read2_b32 v[2:3], v69 offset0:66 offset1:99
	s_lshl_b64 s[6:7], s[16:17], 1
	v_lshl_add_u64 v[6:7], v[6:7], 1, s[0:1]
	s_waitcnt lgkmcnt(0)
	v_cvt_pk_bf16_f32 v1, v2, v3
	ds_read2_b32 v[2:3], v69 offset0:132 offset1:165
	v_mov_b32_e32 v35, v129
	v_lshl_add_u64 v[6:7], v[6:7], 0, s[6:7]
	s_waitcnt lgkmcnt(0)
	v_cvt_pk_bf16_f32 v2, v2, v3
	ds_read2_b32 v[4:5], v69 offset0:198 offset1:231
	s_waitcnt lgkmcnt(0)
	v_cvt_pk_bf16_f32 v3, v4, v5
	v_lshl_add_u64 v[6:7], v[6:7], 0, v[34:35]
	ds_read2_b32 v[4:5], v69 offset0:8 offset1:41
	global_store_dwordx4 v[6:7], v[0:3], off sc1
	s_mov_b32 s16, s5
	s_waitcnt vmcnt(54)
	v_mov_b32_e32 v14, v74
	s_waitcnt lgkmcnt(0)
	v_cvt_pk_bf16_f32 v0, v4, v5
	ds_read2_b32 v[2:3], v69 offset0:74 offset1:107
	s_waitcnt lgkmcnt(0)
	v_cvt_pk_bf16_f32 v1, v2, v3
	ds_read2_b32 v[2:3], v69 offset0:140 offset1:173
	s_waitcnt lgkmcnt(0)
	v_cvt_pk_bf16_f32 v2, v2, v3
	v_add_u32_e32 v3, s2, v70
	v_mul_hi_i32_i24_e32 v7, s4, v3
	v_mul_i32_i24_e32 v6, s4, v3
	v_lshl_add_u64 v[6:7], v[6:7], 1, s[0:1]
	v_lshl_add_u64 v[6:7], v[6:7], 0, s[6:7]
	ds_read2_b32 v[4:5], v69 offset0:206 offset1:239
	s_waitcnt lgkmcnt(0)
	v_cvt_pk_bf16_f32 v3, v4, v5
	v_lshl_add_u64 v[6:7], v[6:7], 0, v[34:35]
	ds_read2_b32 v[4:5], v69 offset0:16 offset1:49
	global_store_dwordx4 v[6:7], v[0:3], off sc1
	v_mov_b32_e32 v15, v59
	s_waitcnt vmcnt(18)
	v_mov_b32_e32 v59, v106
	s_waitcnt lgkmcnt(0)
	v_cvt_pk_bf16_f32 v0, v4, v5
	ds_read2_b32 v[2:3], v69 offset0:82 offset1:115
	s_waitcnt lgkmcnt(0)
	v_cvt_pk_bf16_f32 v1, v2, v3
	ds_read2_b32 v[2:3], v69 offset0:148 offset1:181
	s_waitcnt lgkmcnt(0)
	v_cvt_pk_bf16_f32 v2, v2, v3
	v_add_u32_e32 v3, s2, v71
	v_mul_hi_i32_i24_e32 v7, s4, v3
	v_mul_i32_i24_e32 v6, s4, v3
	v_lshl_add_u64 v[6:7], v[6:7], 1, s[0:1]
	ds_read2_b32 v[4:5], v69 offset0:214 offset1:247
	v_lshl_add_u64 v[6:7], v[6:7], 0, s[6:7]
	s_waitcnt lgkmcnt(0)
	v_cvt_pk_bf16_f32 v3, v4, v5
	ds_read2_b32 v[4:5], v69 offset0:24 offset1:57
	v_lshl_add_u64 v[6:7], v[6:7], 0, v[34:35]
	global_store_dwordx4 v[6:7], v[0:3], off sc1
	v_mov_b32_e32 v74, v105
	v_mov_b32_e32 v13, v46
	s_waitcnt lgkmcnt(0)
	v_cvt_pk_bf16_f32 v0, v4, v5
	v_add_u32_e32 v4, s2, v72
	v_mul_hi_i32_i24_e32 v5, s4, v4
	v_mul_i32_i24_e32 v4, s4, v4
	v_lshl_add_u64 v[4:5], v[4:5], 1, s[0:1]
	ds_read2_b32 v[2:3], v69 offset0:90 offset1:123
	v_lshl_add_u64 v[4:5], v[4:5], 0, s[6:7]
	s_waitcnt lgkmcnt(0)
	v_cvt_pk_bf16_f32 v1, v2, v3
	ds_read2_b32 v[2:3], v69 offset0:156 offset1:189
	v_lshl_add_u64 v[4:5], v[4:5], 0, v[34:35]
	s_waitcnt lgkmcnt(0)
	v_cvt_pk_bf16_f32 v2, v2, v3
	ds_read2_b32 v[6:7], v69 offset0:222 offset1:255
	s_waitcnt lgkmcnt(0)
	v_cvt_pk_bf16_f32 v3, v6, v7
	global_store_dwordx4 v[4:5], v[0:3], off sc1
	s_waitcnt lgkmcnt(0)
	s_add_i32 s2, s93, s94
	s_mov_b64 s[4:5], s[10:11]
	v_mov_b32_e32 v46, v104
	v_mov_b32_e32 v12, v48
	v_mov_b32_e32 v48, v103
	v_mov_b32_e32 v11, v47
	v_mov_b32_e32 v47, v102
	v_mov_b32_e32 v10, v49
	v_mov_b32_e32 v49, v101
	v_mov_b32_e32 v9, v50
	v_mov_b32_e32 v50, v100
	v_mov_b32_e32 v8, v51
	v_mov_b32_e32 v51, v99
	v_mov_b32_e32 v7, v52
	v_mov_b32_e32 v52, v82
	s_cmpk_lt_i32 s2, 0x2b00
	v_mov_b32_e32 v6, v53
	v_mov_b32_e32 v53, v81
	v_mov_b32_e32 v5, v54
	v_mov_b32_e32 v54, v80
	v_mov_b32_e32 v4, v55
	v_mov_b32_e32 v55, v79
	v_mov_b32_e32 v3, v56
	v_mov_b32_e32 v56, v78
	v_mov_b32_e32 v2, v57
	v_mov_b32_e32 v57, v77
	v_mov_b32_e32 v1, v58
	v_mov_b32_e32 v58, v76
	v_mov_b32_e32 v0, v67
	v_mov_b32_e32 v67, v75
	v_mov_b32_e32 v16, v45
	s_waitcnt vmcnt(19)
	v_mov_b32_e32 v45, v83
	v_mov_b32_e32 v17, v44
	s_waitcnt vmcnt(18)
	v_mov_b32_e32 v44, v84
	v_mov_b32_e32 v18, v43
	s_waitcnt vmcnt(17)
	v_mov_b32_e32 v43, v85
	v_mov_b32_e32 v19, v42
	s_waitcnt vmcnt(16)
	v_mov_b32_e32 v42, v86
	v_mov_b32_e32 v20, v41
	s_waitcnt vmcnt(15)
	v_mov_b32_e32 v41, v87
	v_mov_b32_e32 v21, v40
	s_waitcnt vmcnt(14)
	v_mov_b32_e32 v40, v88
	v_mov_b32_e32 v22, v39
	s_waitcnt vmcnt(13)
	v_mov_b32_e32 v39, v89
	v_mov_b32_e32 v23, v38
	s_waitcnt vmcnt(12)
	v_mov_b32_e32 v38, v90
	v_mov_b32_e32 v24, v37
	s_waitcnt vmcnt(11)
	v_mov_b32_e32 v37, v91
	v_mov_b32_e32 v25, v66
	s_waitcnt vmcnt(10)
	v_mov_b32_e32 v66, v92
	v_mov_b32_e32 v26, v65
	s_waitcnt vmcnt(9)
	v_mov_b32_e32 v65, v93
	v_mov_b32_e32 v27, v64
	s_waitcnt vmcnt(8)
	v_mov_b32_e32 v64, v94
	v_mov_b32_e32 v28, v63
	s_waitcnt vmcnt(7)
	v_mov_b32_e32 v63, v95
	v_mov_b32_e32 v29, v62
	s_waitcnt vmcnt(6)
	v_mov_b32_e32 v62, v96
	v_mov_b32_e32 v30, v61
	s_waitcnt vmcnt(5)
	v_mov_b32_e32 v61, v97
	v_mov_b32_e32 v31, v60
	s_waitcnt vmcnt(4)
	v_mov_b32_e32 v60, v98
	s_mov_b32 s2, s18
	s_mov_b64 s[14:15], s[12:13]
	s_mov_b64 s[0:1], s[8:9]
	s_mov_b32 s18, s74
	s_mov_b32 s5, s19
	s_mov_b64 s[10:11], s[70:71]
	s_mov_b64 s[12:13], s[68:69]
	s_mov_b64 s[8:9], s[22:23]
	s_cbranch_scc0 .LBB0_631
